# post phase (groupnorm+bonus+gate): operands of 4 items loaded per batch behind one wait instead of one exposed round trip per item; gn weights loaded once
# speedup vs baseline: 1.0037x; 1.0001x over previous
.LBB0_857:
	global_load_dwordx4 v[40:43], v[2:3], off
	global_load_dwordx4 v[44:47], v[4:5], off
	v_mov_b32_e32 v96, v7
	v_mov_b32_e32 v83, 0
	s_mov_b32 s14, 16
.Lpost_loop:
	v_ashrrev_i32_e32 v90, 4, v96
	v_ashrrev_i32_e32 v91, 31, v90
	v_lshlrev_b64 v[92:93], 11, v[90:91]
	v_lshl_or_b32 v92, v6, 1, v92
	v_lshlrev_b64 v[90:91], 6, v[90:91]
	v_lshl_add_u64 v[94:95], s[6:7], 0, v[92:93]
	v_lshl_add_u64 v[90:91], v[0:1], 0, v[90:91]
	v_lshl_add_u64 v[56:57], s[4:5], 0, v[92:93]
	v_lshl_add_u64 v[92:93], s[8:9], 0, v[92:93]
	global_load_dwordx2 v[48:49], v[94:95], off
	global_load_dwordx2 v[50:51], v[56:57], off
	global_load_dwordx2 v[52:53], v[92:93], off
	global_load_dword v54, v[90:91], off
	v_add_u32_e32 v96, s12, v96
	v_ashrrev_i32_e32 v90, 4, v96
	v_ashrrev_i32_e32 v91, 31, v90
	v_lshlrev_b64 v[92:93], 11, v[90:91]
	v_lshl_or_b32 v92, v6, 1, v92
	v_lshlrev_b64 v[90:91], 6, v[90:91]
	v_lshl_add_u64 v[94:95], s[6:7], 0, v[92:93]
	v_lshl_add_u64 v[90:91], v[0:1], 0, v[90:91]
	v_lshl_add_u64 v[66:67], s[4:5], 0, v[92:93]
	v_lshl_add_u64 v[92:93], s[8:9], 0, v[92:93]
	global_load_dwordx2 v[58:59], v[94:95], off
	global_load_dwordx2 v[60:61], v[66:67], off
	global_load_dwordx2 v[62:63], v[92:93], off
	global_load_dword v64, v[90:91], off
	v_add_u32_e32 v96, s12, v96
	v_ashrrev_i32_e32 v90, 4, v96
	v_ashrrev_i32_e32 v91, 31, v90
	v_lshlrev_b64 v[92:93], 11, v[90:91]
	v_lshl_or_b32 v92, v6, 1, v92
	v_lshlrev_b64 v[90:91], 6, v[90:91]
	v_lshl_add_u64 v[94:95], s[6:7], 0, v[92:93]
	v_lshl_add_u64 v[90:91], v[0:1], 0, v[90:91]
	v_lshl_add_u64 v[76:77], s[4:5], 0, v[92:93]
	v_lshl_add_u64 v[92:93], s[8:9], 0, v[92:93]
	global_load_dwordx2 v[68:69], v[94:95], off
	global_load_dwordx2 v[70:71], v[76:77], off
	global_load_dwordx2 v[72:73], v[92:93], off
	global_load_dword v74, v[90:91], off
	v_add_u32_e32 v96, s12, v96
	v_ashrrev_i32_e32 v90, 4, v96
	v_ashrrev_i32_e32 v91, 31, v90
	v_lshlrev_b64 v[92:93], 11, v[90:91]
	v_lshl_or_b32 v92, v6, 1, v92
	v_lshlrev_b64 v[90:91], 6, v[90:91]
	v_lshl_add_u64 v[94:95], s[6:7], 0, v[92:93]
	v_lshl_add_u64 v[90:91], v[0:1], 0, v[90:91]
	v_lshl_add_u64 v[86:87], s[4:5], 0, v[92:93]
	v_lshl_add_u64 v[92:93], s[8:9], 0, v[92:93]
	global_load_dwordx2 v[78:79], v[94:95], off
	global_load_dwordx2 v[80:81], v[86:87], off
	global_load_dwordx2 v[82:83], v[92:93], off
	global_load_dword v84, v[90:91], off
	v_add_u32_e32 v96, s12, v96
	s_waitcnt vmcnt(0)
	v_mov_b32_e32 v26, v48
	v_mov_b32_e32 v27, v49
	v_mov_b32_e32 v28, v50
	v_mov_b32_e32 v29, v51
	v_mov_b32_e32 v30, v52
	v_mov_b32_e32 v31, v53
	v_mov_b32_e32 v32, v54
	v_mov_b32_e32 v22, v56
	v_mov_b32_e32 v23, v57
	v_mov_b32_e32 v10, v40
	v_mov_b32_e32 v11, v41
	v_mov_b32_e32 v12, v42
	v_mov_b32_e32 v13, v43
	v_mov_b32_e32 v14, v44
	v_mov_b32_e32 v15, v45
	v_mov_b32_e32 v16, v46
	v_mov_b32_e32 v17, v47
	v_lshlrev_b32_e32 v18, 16, v26
	v_and_b32_e32 v19, 0xffff0000, v26
	v_lshlrev_b32_e32 v20, 16, v27
	v_and_b32_e32 v21, 0xffff0000, v27
	v_lshlrev_b32_e32 v24, 16, v30
	v_and_b32_e32 v25, 0xffff0000, v30
	v_lshlrev_b32_e32 v26, 16, v31
	v_and_b32_e32 v27, 0xffff0000, v31
	v_lshlrev_b32_e32 v31, 16, v29
	v_lshlrev_b32_e32 v30, 16, v28
	v_and_b32_e32 v29, 0xffff0000, v29
	v_and_b32_e32 v28, 0xffff0000, v28
	v_pk_add_f32 v[34:35], v[30:31], v[28:29]
	s_nop 0
	v_add_f32_e32 v9, v34, v35
	s_nop 1
	v_add_f32_dpp v9, v9, v9 quad_perm:[1,0,3,2] row_mask:0xf bank_mask:0xf bound_ctrl:1
	s_nop 1
	v_add_f32_dpp v9, v9, v9 quad_perm:[2,3,0,1] row_mask:0xf bank_mask:0xf bound_ctrl:1
	s_nop 1
	v_add_f32_dpp v9, v9, v9 row_half_mirror row_mask:0xf bank_mask:0xf bound_ctrl:1
	s_nop 1
	v_add_f32_dpp v9, v9, v9 row_mirror row_mask:0xf bank_mask:0xf bound_ctrl:1
	v_fmac_f32_e32 v28, 0xbc800000, v9
	v_fmac_f32_e32 v29, 0xbc800000, v9
	v_fmac_f32_e32 v31, 0xbc800000, v9
	v_fmac_f32_e32 v30, 0xbc800000, v9
	v_mov_b32_e32 v34, v31
	v_mov_b32_e32 v35, v29
	v_mov_b32_e32 v31, v28
	v_pk_mul_f32 v[28:29], v[34:35], v[34:35]
	v_pk_mul_f32 v[36:37], v[30:31], v[30:31]
	s_nop 0
	v_pk_mov_b32 v[38:39], v[36:37], v[28:29] op_sel:[1,0]
	v_mov_b32_e32 v37, v29
	v_pk_add_f32 v[28:29], v[38:39], v[36:37]
	s_nop 0
	v_add_f32_e32 v9, v28, v29
	s_nop 1
	v_add_f32_dpp v9, v9, v9 quad_perm:[1,0,3,2] row_mask:0xf bank_mask:0xf bound_ctrl:1
	s_nop 1
	v_add_f32_dpp v9, v9, v9 quad_perm:[2,3,0,1] row_mask:0xf bank_mask:0xf bound_ctrl:1
	s_nop 1
	v_add_f32_dpp v9, v9, v9 row_half_mirror row_mask:0xf bank_mask:0xf bound_ctrl:1
	s_nop 1
	v_add_f32_dpp v9, v9, v9 row_mirror row_mask:0xf bank_mask:0xf bound_ctrl:1
	v_fmamk_f32 v9, v9, 0x3c800000, v8
	v_rsq_f32_e32 v28, v9
	s_nop 0
	v_pk_mul_f32 v[30:31], v[30:31], v[28:29] op_sel_hi:[1,0]
	v_pk_mul_f32 v[28:29], v[34:35], v[28:29] op_sel_hi:[1,0]
	v_pk_fma_f32 v[10:11], v[10:11], v[30:31], v[14:15]
	v_pk_fma_f32 v[12:13], v[12:13], v[28:29], v[16:17]
	v_pk_fma_f32 v[10:11], v[32:33], v[18:19], v[10:11] op_sel_hi:[0,1,1]
	v_pk_fma_f32 v[12:13], v[32:33], v[20:21], v[12:13] op_sel_hi:[0,1,1]
	v_pk_mul_f32 v[10:11], v[10:11], v[24:25]
	v_pk_mul_f32 v[12:13], v[12:13], v[26:27]
	v_cvt_pk_bf16_f32 v10, v10, v11
	s_nop 0
	v_cvt_pk_bf16_f32 v11, v12, v13
	global_store_dwordx2 v[22:23], v[10:11], off
	v_mov_b32_e32 v26, v58
	v_mov_b32_e32 v27, v59
	v_mov_b32_e32 v28, v60
	v_mov_b32_e32 v29, v61
	v_mov_b32_e32 v30, v62
	v_mov_b32_e32 v31, v63
	v_mov_b32_e32 v32, v64
	v_mov_b32_e32 v22, v66
	v_mov_b32_e32 v23, v67
	v_mov_b32_e32 v10, v40
	v_mov_b32_e32 v11, v41
	v_mov_b32_e32 v12, v42
	v_mov_b32_e32 v13, v43
	v_mov_b32_e32 v14, v44
	v_mov_b32_e32 v15, v45
	v_mov_b32_e32 v16, v46
	v_mov_b32_e32 v17, v47
	v_lshlrev_b32_e32 v18, 16, v26
	v_and_b32_e32 v19, 0xffff0000, v26
	v_lshlrev_b32_e32 v20, 16, v27
	v_and_b32_e32 v21, 0xffff0000, v27
	v_lshlrev_b32_e32 v24, 16, v30
	v_and_b32_e32 v25, 0xffff0000, v30
	v_lshlrev_b32_e32 v26, 16, v31
	v_and_b32_e32 v27, 0xffff0000, v31
	v_lshlrev_b32_e32 v31, 16, v29
	v_lshlrev_b32_e32 v30, 16, v28
	v_and_b32_e32 v29, 0xffff0000, v29
	v_and_b32_e32 v28, 0xffff0000, v28
	v_pk_add_f32 v[34:35], v[30:31], v[28:29]
	s_nop 0
	v_add_f32_e32 v9, v34, v35
	s_nop 1
	v_add_f32_dpp v9, v9, v9 quad_perm:[1,0,3,2] row_mask:0xf bank_mask:0xf bound_ctrl:1
	s_nop 1
	v_add_f32_dpp v9, v9, v9 quad_perm:[2,3,0,1] row_mask:0xf bank_mask:0xf bound_ctrl:1
	s_nop 1
	v_add_f32_dpp v9, v9, v9 row_half_mirror row_mask:0xf bank_mask:0xf bound_ctrl:1
	s_nop 1
	v_add_f32_dpp v9, v9, v9 row_mirror row_mask:0xf bank_mask:0xf bound_ctrl:1
	v_fmac_f32_e32 v28, 0xbc800000, v9
	v_fmac_f32_e32 v29, 0xbc800000, v9
	v_fmac_f32_e32 v31, 0xbc800000, v9
	v_fmac_f32_e32 v30, 0xbc800000, v9
	v_mov_b32_e32 v34, v31
	v_mov_b32_e32 v35, v29
	v_mov_b32_e32 v31, v28
	v_pk_mul_f32 v[28:29], v[34:35], v[34:35]
	v_pk_mul_f32 v[36:37], v[30:31], v[30:31]
	s_nop 0
	v_pk_mov_b32 v[38:39], v[36:37], v[28:29] op_sel:[1,0]
	v_mov_b32_e32 v37, v29
	v_pk_add_f32 v[28:29], v[38:39], v[36:37]
	s_nop 0
	v_add_f32_e32 v9, v28, v29
	s_nop 1
	v_add_f32_dpp v9, v9, v9 quad_perm:[1,0,3,2] row_mask:0xf bank_mask:0xf bound_ctrl:1
	s_nop 1
	v_add_f32_dpp v9, v9, v9 quad_perm:[2,3,0,1] row_mask:0xf bank_mask:0xf bound_ctrl:1
	s_nop 1
	v_add_f32_dpp v9, v9, v9 row_half_mirror row_mask:0xf bank_mask:0xf bound_ctrl:1
	s_nop 1
	v_add_f32_dpp v9, v9, v9 row_mirror row_mask:0xf bank_mask:0xf bound_ctrl:1
	v_fmamk_f32 v9, v9, 0x3c800000, v8
	v_rsq_f32_e32 v28, v9
	s_nop 0
	v_pk_mul_f32 v[30:31], v[30:31], v[28:29] op_sel_hi:[1,0]
	v_pk_mul_f32 v[28:29], v[34:35], v[28:29] op_sel_hi:[1,0]
	v_pk_fma_f32 v[10:11], v[10:11], v[30:31], v[14:15]
	v_pk_fma_f32 v[12:13], v[12:13], v[28:29], v[16:17]
	v_pk_fma_f32 v[10:11], v[32:33], v[18:19], v[10:11] op_sel_hi:[0,1,1]
	v_pk_fma_f32 v[12:13], v[32:33], v[20:21], v[12:13] op_sel_hi:[0,1,1]
	v_pk_mul_f32 v[10:11], v[10:11], v[24:25]
	v_pk_mul_f32 v[12:13], v[12:13], v[26:27]
	v_cvt_pk_bf16_f32 v10, v10, v11
	s_nop 0
	v_cvt_pk_bf16_f32 v11, v12, v13
	global_store_dwordx2 v[22:23], v[10:11], off
	v_mov_b32_e32 v26, v68
	v_mov_b32_e32 v27, v69
	v_mov_b32_e32 v28, v70
	v_mov_b32_e32 v29, v71
	v_mov_b32_e32 v30, v72
	v_mov_b32_e32 v31, v73
	v_mov_b32_e32 v32, v74
	v_mov_b32_e32 v22, v76
	v_mov_b32_e32 v23, v77
	v_mov_b32_e32 v10, v40
	v_mov_b32_e32 v11, v41
	v_mov_b32_e32 v12, v42
	v_mov_b32_e32 v13, v43
	v_mov_b32_e32 v14, v44
	v_mov_b32_e32 v15, v45
	v_mov_b32_e32 v16, v46
	v_mov_b32_e32 v17, v47
	v_lshlrev_b32_e32 v18, 16, v26
	v_and_b32_e32 v19, 0xffff0000, v26
	v_lshlrev_b32_e32 v20, 16, v27
	v_and_b32_e32 v21, 0xffff0000, v27
	v_lshlrev_b32_e32 v24, 16, v30
	v_and_b32_e32 v25, 0xffff0000, v30
	v_lshlrev_b32_e32 v26, 16, v31
	v_and_b32_e32 v27, 0xffff0000, v31
	v_lshlrev_b32_e32 v31, 16, v29
	v_lshlrev_b32_e32 v30, 16, v28
	v_and_b32_e32 v29, 0xffff0000, v29
	v_and_b32_e32 v28, 0xffff0000, v28
	v_pk_add_f32 v[34:35], v[30:31], v[28:29]
	s_nop 0
	v_add_f32_e32 v9, v34, v35
	s_nop 1
	v_add_f32_dpp v9, v9, v9 quad_perm:[1,0,3,2] row_mask:0xf bank_mask:0xf bound_ctrl:1
	s_nop 1
	v_add_f32_dpp v9, v9, v9 quad_perm:[2,3,0,1] row_mask:0xf bank_mask:0xf bound_ctrl:1
	s_nop 1
	v_add_f32_dpp v9, v9, v9 row_half_mirror row_mask:0xf bank_mask:0xf bound_ctrl:1
	s_nop 1
	v_add_f32_dpp v9, v9, v9 row_mirror row_mask:0xf bank_mask:0xf bound_ctrl:1
	v_fmac_f32_e32 v28, 0xbc800000, v9
	v_fmac_f32_e32 v29, 0xbc800000, v9
	v_fmac_f32_e32 v31, 0xbc800000, v9
	v_fmac_f32_e32 v30, 0xbc800000, v9
	v_mov_b32_e32 v34, v31
	v_mov_b32_e32 v35, v29
	v_mov_b32_e32 v31, v28
	v_pk_mul_f32 v[28:29], v[34:35], v[34:35]
	v_pk_mul_f32 v[36:37], v[30:31], v[30:31]
	s_nop 0
	v_pk_mov_b32 v[38:39], v[36:37], v[28:29] op_sel:[1,0]
	v_mov_b32_e32 v37, v29
	v_pk_add_f32 v[28:29], v[38:39], v[36:37]
	s_nop 0
	v_add_f32_e32 v9, v28, v29
	s_nop 1
	v_add_f32_dpp v9, v9, v9 quad_perm:[1,0,3,2] row_mask:0xf bank_mask:0xf bound_ctrl:1
	s_nop 1
	v_add_f32_dpp v9, v9, v9 quad_perm:[2,3,0,1] row_mask:0xf bank_mask:0xf bound_ctrl:1
	s_nop 1
	v_add_f32_dpp v9, v9, v9 row_half_mirror row_mask:0xf bank_mask:0xf bound_ctrl:1
	s_nop 1
	v_add_f32_dpp v9, v9, v9 row_mirror row_mask:0xf bank_mask:0xf bound_ctrl:1
	v_fmamk_f32 v9, v9, 0x3c800000, v8
	v_rsq_f32_e32 v28, v9
	s_nop 0
	v_pk_mul_f32 v[30:31], v[30:31], v[28:29] op_sel_hi:[1,0]
	v_pk_mul_f32 v[28:29], v[34:35], v[28:29] op_sel_hi:[1,0]
	v_pk_fma_f32 v[10:11], v[10:11], v[30:31], v[14:15]
	v_pk_fma_f32 v[12:13], v[12:13], v[28:29], v[16:17]
	v_pk_fma_f32 v[10:11], v[32:33], v[18:19], v[10:11] op_sel_hi:[0,1,1]
	v_pk_fma_f32 v[12:13], v[32:33], v[20:21], v[12:13] op_sel_hi:[0,1,1]
	v_pk_mul_f32 v[10:11], v[10:11], v[24:25]
	v_pk_mul_f32 v[12:13], v[12:13], v[26:27]
	v_cvt_pk_bf16_f32 v10, v10, v11
	s_nop 0
	v_cvt_pk_bf16_f32 v11, v12, v13
	global_store_dwordx2 v[22:23], v[10:11], off
	v_mov_b32_e32 v26, v78
	v_mov_b32_e32 v27, v79
	v_mov_b32_e32 v28, v80
	v_mov_b32_e32 v29, v81
	v_mov_b32_e32 v30, v82
	v_mov_b32_e32 v31, v83
	v_mov_b32_e32 v32, v84
	v_mov_b32_e32 v22, v86
	v_mov_b32_e32 v23, v87
	v_mov_b32_e32 v10, v40
	v_mov_b32_e32 v11, v41
	v_mov_b32_e32 v12, v42
	v_mov_b32_e32 v13, v43
	v_mov_b32_e32 v14, v44
	v_mov_b32_e32 v15, v45
	v_mov_b32_e32 v16, v46
	v_mov_b32_e32 v17, v47
	v_lshlrev_b32_e32 v18, 16, v26
	v_and_b32_e32 v19, 0xffff0000, v26
	v_lshlrev_b32_e32 v20, 16, v27
	v_and_b32_e32 v21, 0xffff0000, v27
	v_lshlrev_b32_e32 v24, 16, v30
	v_and_b32_e32 v25, 0xffff0000, v30
	v_lshlrev_b32_e32 v26, 16, v31
	v_and_b32_e32 v27, 0xffff0000, v31
	v_lshlrev_b32_e32 v31, 16, v29
	v_lshlrev_b32_e32 v30, 16, v28
	v_and_b32_e32 v29, 0xffff0000, v29
	v_and_b32_e32 v28, 0xffff0000, v28
	v_pk_add_f32 v[34:35], v[30:31], v[28:29]
	s_nop 0
	v_add_f32_e32 v9, v34, v35
	s_nop 1
	v_add_f32_dpp v9, v9, v9 quad_perm:[1,0,3,2] row_mask:0xf bank_mask:0xf bound_ctrl:1
	s_nop 1
	v_add_f32_dpp v9, v9, v9 quad_perm:[2,3,0,1] row_mask:0xf bank_mask:0xf bound_ctrl:1
	s_nop 1
	v_add_f32_dpp v9, v9, v9 row_half_mirror row_mask:0xf bank_mask:0xf bound_ctrl:1
	s_nop 1
	v_add_f32_dpp v9, v9, v9 row_mirror row_mask:0xf bank_mask:0xf bound_ctrl:1
	v_fmac_f32_e32 v28, 0xbc800000, v9
	v_fmac_f32_e32 v29, 0xbc800000, v9
	v_fmac_f32_e32 v31, 0xbc800000, v9
	v_fmac_f32_e32 v30, 0xbc800000, v9
	v_mov_b32_e32 v34, v31
	v_mov_b32_e32 v35, v29
	v_mov_b32_e32 v31, v28
	v_pk_mul_f32 v[28:29], v[34:35], v[34:35]
	v_pk_mul_f32 v[36:37], v[30:31], v[30:31]
	s_nop 0
	v_pk_mov_b32 v[38:39], v[36:37], v[28:29] op_sel:[1,0]
	v_mov_b32_e32 v37, v29
	v_pk_add_f32 v[28:29], v[38:39], v[36:37]
	s_nop 0
	v_add_f32_e32 v9, v28, v29
	s_nop 1
	v_add_f32_dpp v9, v9, v9 quad_perm:[1,0,3,2] row_mask:0xf bank_mask:0xf bound_ctrl:1
	s_nop 1
	v_add_f32_dpp v9, v9, v9 quad_perm:[2,3,0,1] row_mask:0xf bank_mask:0xf bound_ctrl:1
	s_nop 1
	v_add_f32_dpp v9, v9, v9 row_half_mirror row_mask:0xf bank_mask:0xf bound_ctrl:1
	s_nop 1
	v_add_f32_dpp v9, v9, v9 row_mirror row_mask:0xf bank_mask:0xf bound_ctrl:1
	v_fmamk_f32 v9, v9, 0x3c800000, v8
	v_rsq_f32_e32 v28, v9
	s_nop 0
	v_pk_mul_f32 v[30:31], v[30:31], v[28:29] op_sel_hi:[1,0]
	v_pk_mul_f32 v[28:29], v[34:35], v[28:29] op_sel_hi:[1,0]
	v_pk_fma_f32 v[10:11], v[10:11], v[30:31], v[14:15]
	v_pk_fma_f32 v[12:13], v[12:13], v[28:29], v[16:17]
	v_pk_fma_f32 v[10:11], v[32:33], v[18:19], v[10:11] op_sel_hi:[0,1,1]
	v_pk_fma_f32 v[12:13], v[32:33], v[20:21], v[12:13] op_sel_hi:[0,1,1]
	v_pk_mul_f32 v[10:11], v[10:11], v[24:25]
	v_pk_mul_f32 v[12:13], v[12:13], v[26:27]
	v_cvt_pk_bf16_f32 v10, v10, v11
	s_nop 0
	v_cvt_pk_bf16_f32 v11, v12, v13
	global_store_dwordx2 v[22:23], v[10:11], off
	s_sub_u32 s14, s14, 1
	s_cmp_lg_u32 s14, 0
	s_cbranch_scc1 .Lpost_loop
	s_or_b64 exec, exec, s[10:11]
	s_load_dwordx2 s[4:5], s[0:1], 0x120
	s_waitcnt lgkmcnt(0)
	v_mov_b32_e32 v0, s4
	v_mov_b32_e32 v1, s5
